# P0: weight transposes now shared uniformly by all 512 blocks (adaLN GEMV blocks no longer skip them, since the GEMV is short now)
# speedup vs baseline: 1.0181x; 1.0031x over previous
.LBB0_51:
	s_mov_b64 s[0:1], -1
